# E36 knorm task: both gain-vector loads issued with the raw-K load instead of after the reduction (on top of E34)
# baseline (speedup 1.0000x reference)
; __device__ __forceinline__ unsigned cvt_pk_bf16(float lo, float hi) { f32x2 v = {lo, hi}; bf16x2_t b = __builtin_convertvector(v, bf16x2_t); return __builtin_bit_cast(unsigned, b); }
; __device__ __forceinline__ void knorm_task(int task, const float* kraw, const float* kg_all, const float* qg_all, bf16_t* KP, int lane) {
;     const int head = task & 3, row = (task >> 2) & 511, lay = task >> 11;
;     const f32x4 v = *(const f32x4*)(kraw + ((size_t)lay * 512 + row) * 1024 + head * 256 + 4 * lane);
;     const float ss = wave_sum((v.x * v.x + v.y * v.y) + (v.z * v.z + v.w * v.w));
;     const float rs = __builtin_amdgcn_rsqf(ss * (1.f / 256.f) + EPS);
;     const f32x4 kg = *(const f32x4*)(kg_all + lay * 256 + 4 * lane), qg = *(const f32x4*)(qg_all + lay * 256 + 4 * lane);
;     const int b = row >> 8, mt = row & 255;
;     u32x2 w; w.x = cvt_pk_bf16(v.x * rs * kg.x * qg.x, v.y * rs * kg.y * qg.y); w.y = cvt_pk_bf16(v.z * rs * kg.z * qg.z, v.w * rs * kg.w * qg.w);
;     *(u32x2*)(KP + ((size_t)((lay * 2 + b) * 4 + head) * 256 + mt) * 256 + 4 * lane) = w;
; }
.LBB0_442:
	s_mov_b32 s2, s24
	v_lshlrev_b64 v[10:11], 2, v[0:1]
	v_mov_b32_e32 v2, s2
	ds_read_b64 v[2:3], v2
	s_mov_b32 s2, s25
	v_cmp_eq_u32_e32 vcc, 0, v214
	s_waitcnt lgkmcnt(0)
	v_readfirstlane_b32 s19, v2
	v_mov_b32_e32 v2, s2
	s_ashr_i32 s2, s54, 11
	s_ashr_i32 s3, s2, 31
	s_lshl_b64 s[10:11], s[2:3], 21
	s_add_u32 s3, s12, s10
	s_addc_u32 s10, s13, s11
	s_lshl_b32 s11, s54, 10
	v_readfirstlane_b32 s18, v3
	ds_read_b64 v[2:3], v2
	s_and_b32 s11, s11, 0x1ff000
	s_add_u32 s3, s3, s11
	s_addc_u32 s11, s10, 0
	s_add_u32 s10, s3, s17
	s_addc_u32 s11, s11, 0
	s_waitcnt lgkmcnt(0)
	v_readfirstlane_b32 s20, v3
	v_readfirstlane_b32 s21, v2
	v_lshl_add_u64 v[2:3], s[10:11], 0, v[10:11]
	global_load_dwordx4 v[2:5], v[2:3], off
	s_lshl_b32 s10, s2, 8
	s_ashr_i32 s11, s10, 31
	s_lshl_b64 s[10:11], s[10:11], 2
	s_add_u32 s22, s19, s10
	s_addc_u32 s23, s18, s11
	s_add_u32 s10, s21, s10
	s_addc_u32 s11, s20, s11
	v_lshl_add_u64 v[16:17], s[22:23], 0, v[10:11]
	global_load_dwordx4 v[16:19], v[16:17], off
	v_lshl_add_u64 v[20:21], s[10:11], 0, v[10:11]
	global_load_dwordx4 v[20:23], v[20:21], off
	s_lshr_b32 s3, s54, 8
	s_lshl_b32 s2, s2, 3
	s_and_b32 s3, s3, 4
	s_or_b32 s2, s2, s3
	s_or_b32 s2, s2, s16
	s_ashr_i32 s3, s2, 31
	s_lshl_b64 s[2:3], s[2:3], 17
	s_add_u32 s2, s14, s2
	s_addc_u32 s3, s15, s3
	s_waitcnt vmcnt(2)
	v_pk_mul_f32 v[6:7], v[4:5], v[4:5]
	v_pk_mul_f32 v[8:9], v[2:3], v[2:3]
	s_nop 0
	v_pk_mov_b32 v[12:13], v[8:9], v[6:7] op_sel:[1,0]
	v_mov_b32_e32 v9, v7
	v_pk_add_f32 v[6:7], v[12:13], v[8:9]
	s_nop 0
	v_add_f32_e32 v6, v6, v7
	ds_swizzle_b32 v7, v6 offset:swizzle(SWAP,1)
	s_waitcnt lgkmcnt(0)
	v_add_f32_e32 v6, v6, v7
	ds_swizzle_b32 v7, v6 offset:swizzle(SWAP,2)
	s_waitcnt lgkmcnt(0)
	v_add_f32_e32 v6, v6, v7
	ds_swizzle_b32 v7, v6 offset:swizzle(SWAP,4)
	s_waitcnt lgkmcnt(0)
	v_add_f32_e32 v6, v6, v7
	ds_swizzle_b32 v7, v6 offset:swizzle(SWAP,8)
	s_waitcnt lgkmcnt(0)
	v_add_f32_e32 v6, v6, v7
	ds_swizzle_b32 v7, v6 offset:swizzle(SWAP,16)
	s_waitcnt lgkmcnt(0)
	v_add_f32_e32 v6, v6, v7
	v_mov_b32_e32 v7, v6
	v_mov_b32_e32 v8, v6
	s_nop 1
	v_permlane32_swap_b32_e32 v7, v8
	v_cndmask_b32_e32 v7, v7, v8, vcc
	v_add_f32_e32 v6, v6, v7
	v_fmamk_f32 v6, v6, 0x3b800000, v212
	v_rsq_f32_e32 v14, v6
	s_lshl_b32 s10, s54, 7
	v_pk_mul_f32 v[2:3], v[2:3], v[14:15] op_sel_hi:[1,0]
	v_pk_mul_f32 v[4:5], v[4:5], v[14:15] op_sel_hi:[1,0]
	s_and_b32 s10, s10, 0x1fe00
	s_add_u32 s2, s2, s10
	s_addc_u32 s3, s3, 0
	s_add_i32 s54, s54, s92
	s_cmpk_lt_i32 s54, 0x1000
	s_waitcnt vmcnt(1)
	v_pk_mul_f32 v[2:3], v[16:17], v[2:3]
	v_pk_mul_f32 v[4:5], v[18:19], v[4:5]
	s_waitcnt vmcnt(0)
	v_pk_mul_f32 v[2:3], v[20:21], v[2:3]
	v_pk_mul_f32 v[4:5], v[22:23], v[4:5]
	v_cvt_pk_bf16_f32 v2, v2, v3
	v_cvt_pk_bf16_f32 v3, v4, v5
	v_lshl_add_u64 v[4:5], v[0:1], 1, s[2:3]
	global_store_dwordx2 v[4:5], v[2:3], off
	s_cbranch_scc1 .LBB0_442
